# v16 plus attention epilogue: 64 ds_bpermute lane swaps replaced by DPP quad_perm moves
# speedup vs baseline: 1.0034x; 1.0034x over previous
; #define SBAR() __builtin_amdgcn_sched_barrier(0)
; __device__ __forceinline__ void finishSM(f32x16& p0, f32x16& p1, float alpha, f32x16& lacc, bf16x8& pa0, bf16x8& pa1, bf16x8& pa2, bf16x8& pa3) {
;   for (int r = 0; r < 16; ++r) p1[r] = __builtin_amdgcn_exp2f(p1[r]);
;   (void)alpha;
;     ...
;   LADD8(p0, 0); LADD8(p0, 8); LADD8(p1, 0); LADD8(p1, 8);
;     ...
;   PK4(p0, 0, pa0); PK4(p0, 8, pa1); PK4(p1, 0, pa2); PK4(p1, 8, pa3);
;     ...
; }
; template <typename TQ>
; __device__ __forceinline__ void attn_dense_body(const TQ* __restrict__ Qb, const bf16* __restrict__ Kh, const bf16* __restrict__ Vh,
;                                                 bf16* __restrict__ Ob, int seq, char* lds, float mraw) {
;     ...
;   SBAR(); qkt(pB0, pB1, KBUF(bcur), qr, r32, hi, iv);
;   finishSM(pA0, pA1, 1.f, lacc, pa0, pa1, pa2, pa3); SBAR();
;   pv_d0(o, VBUF(bprev), pa0, pa1, pa2, pa3); partialSM_fixed(pB0, pB1, mnC);
;   finishSM(pB0, pB1, 1.f, lacc, pa0, pa1, pa2, pa3); SBAR();
;   pv_d0(o, VBUF(bcur), pa0, pa1, pa2, pa3);
.LBB0_617:
	s_and_b32 s11, s16, 0x3fffffc0
	s_lshl_b32 s11, s11, 2
	s_add_i32 s11, s11, 0
	s_add_i32 s11, s11, 0x18000
	s_add_i32 s12, s27, 0
	v_add_u32_e32 v100, s12, v203
	ds_read_b128 v[96:99], v100 offset:49152
	ds_read_b128 v[162:165], v100 offset:57344
	v_exp_f32_e32 v95, v95
	s_nop 1
	v_add_f32 v190, v190, v173
	v_add_f32 v191, v191, v175
	v_add_f32 v192, v192, v176
	v_add_f32 v193, v193, v177
	v_add_f32 v183, v183, v170
	v_add_f32 v184, v184, v171
	v_add_f32 v185, v185, v172
	v_add_f32 v186, v186, v174
	s_nop 1
	v_add_f32 v194, v194, v211
	v_add_f32 v195, v195, v214
	v_add_f32 v196, v196, v215
	v_add_f32 v197, v197, v216
	v_add_f32 v198, v198, v217
	v_add_f32 v187, v187, v218
	v_add_f32 v188, v188, v209
	v_add_f32 v189, v189, v213
	s_waitcnt lgkmcnt(0)
	v_mfma_f32_32x32x16_bf16 v[112:127], v[96:99], v[158:161], v[0:15]
	v_mfma_f32_32x32x16_bf16 v[96:111], v[162:165], v[158:161], v[0:15]
	v_add_u32_e32 v162, s12, v204
	ds_read_b128 v[158:161], v162 offset:49152
	ds_read_b128 v[162:165], v162 offset:57344
	s_waitcnt lgkmcnt(0)
	v_mfma_f32_32x32x16_bf16 v[112:127], v[158:161], v[154:157], v[112:127]
	v_add_u32_e32 v158, s12, v206
	v_mfma_f32_32x32x16_bf16 v[96:111], v[162:165], v[154:157], v[96:111]
	ds_read_b128 v[154:157], v158 offset:49152
	ds_read_b128 v[158:161], v158 offset:57344
	s_waitcnt lgkmcnt(0)
	v_mfma_f32_32x32x16_bf16 v[112:127], v[154:157], v[150:153], v[112:127]
	v_add_u32_e32 v154, s12, v207
	v_mfma_f32_32x32x16_bf16 v[96:111], v[158:161], v[150:153], v[96:111]
	ds_read_b128 v[150:153], v154 offset:49152
	ds_read_b128 v[154:157], v154 offset:57344
	s_waitcnt lgkmcnt(0)
	v_mfma_f32_32x32x16_bf16 v[112:127], v[150:153], v[146:149], v[112:127]
	v_add_u32_e32 v150, s12, v208
	v_mfma_f32_32x32x16_bf16 v[96:111], v[154:157], v[146:149], v[96:111]
	ds_read_b128 v[146:149], v150 offset:49152
	ds_read_b128 v[150:153], v150 offset:57344
	s_waitcnt lgkmcnt(0)
	v_mfma_f32_32x32x16_bf16 v[112:127], v[146:149], v[142:145], v[112:127]
	v_add_u32_e32 v146, s12, v205
	v_mfma_f32_32x32x16_bf16 v[96:111], v[150:153], v[142:145], v[96:111]
	ds_read_b128 v[142:145], v146 offset:49152
	ds_read_b128 v[146:149], v146 offset:57344
	s_waitcnt lgkmcnt(0)
	v_mfma_f32_32x32x16_bf16 v[112:127], v[142:145], v[138:141], v[112:127]
	v_add_u32_e32 v142, s12, v202
	v_mfma_f32_32x32x16_bf16 v[96:111], v[146:149], v[138:141], v[96:111]
	ds_read_b128 v[138:141], v142 offset:49152
	ds_read_b128 v[142:145], v142 offset:57344
	s_waitcnt lgkmcnt(0)
	v_mfma_f32_32x32x16_bf16 v[112:127], v[138:141], v[134:137], v[112:127]
	v_add_u32_e32 v138, s12, v200
	v_mfma_f32_32x32x16_bf16 v[96:111], v[142:145], v[134:137], v[96:111]
	ds_read_b128 v[134:137], v138 offset:49152
	ds_read_b128 v[138:141], v138 offset:57344
	v_exp_f32_e32 v142, v92
	v_exp_f32_e32 v143, v93
	v_exp_f32_e32 v144, v94
	s_waitcnt lgkmcnt(0)
	v_mfma_f32_32x32x16_bf16 v[112:127], v[134:137], v[130:133], v[112:127]
	v_exp_f32_e32 v134, v84
	v_exp_f32_e32 v135, v85
	v_exp_f32_e32 v136, v86
	v_exp_f32_e32 v137, v87
	v_mfma_f32_32x32x16_bf16 v[96:111], v[138:141], v[130:133], v[96:111]
	v_exp_f32_e32 v130, v80
	v_exp_f32_e32 v131, v81
	v_exp_f32_e32 v132, v82
	v_exp_f32_e32 v133, v83
	v_cvt_pk_bf16_f32 v80, v211, v214
	v_cvt_pk_bf16_f32 v81, v215, v216
	v_cvt_pk_bf16_f32 v82, v217, v218
	v_cvt_pk_bf16_f32 v83, v209, v213
	v_exp_f32_e32 v138, v88
	v_exp_f32_e32 v139, v89
	v_exp_f32_e32 v140, v90
	v_exp_f32_e32 v141, v91
	s_nop 1
	v_add_f32 v190, v190, v138
	v_add_f32 v191, v191, v139
	v_add_f32 v192, v192, v140
	v_add_f32 v193, v193, v141
	v_add_f32 v183, v183, v142
	v_add_f32 v184, v184, v143
	v_add_f32 v185, v185, v144
	v_add_f32 v186, v186, v95
	v_permlane32_swap_b32_e32 v80, v82
	v_permlane32_swap_b32_e32 v81, v83
	v_cvt_pk_bf16_f32 v84, v173, v175
	v_cvt_pk_bf16_f32 v85, v176, v177
	v_cvt_pk_bf16_f32 v86, v170, v171
	v_cvt_pk_bf16_f32 v87, v172, v174
	v_cvt_pk_bf16_f32 v88, v130, v131
	v_cvt_pk_bf16_f32 v89, v132, v133
	v_cvt_pk_bf16_f32 v90, v134, v135
	v_cvt_pk_bf16_f32 v91, v136, v137
	v_cvt_pk_bf16_f32 v92, v138, v139
	v_cvt_pk_bf16_f32 v93, v140, v141
	v_cvt_pk_bf16_f32 v94, v142, v143
	v_cvt_pk_bf16_f32 v95, v144, v95
	s_nop 1
	v_add_f32 v194, v194, v130
	v_add_f32 v195, v195, v131
	v_add_f32 v196, v196, v132
	v_add_f32 v197, v197, v133
	v_add_f32 v198, v198, v134
	v_add_f32 v187, v187, v135
	v_add_f32 v188, v188, v136
	v_add_f32 v189, v189, v137
	s_nop 0
	v_permlane32_swap_b32_e32 v84, v86
	v_permlane32_swap_b32_e32 v85, v87
	v_permlane32_swap_b32_e32 v88, v90
	v_permlane32_swap_b32_e32 v89, v91
	v_permlane32_swap_b32_e32 v92, v94
	v_permlane32_swap_b32_e32 v93, v95
	v_add_u32_e32 v146, s25, v199
	ds_read_b64_tr_b16 v[130:131], v146 offset:0
	ds_read_b64_tr_b16 v[132:133], v146 offset:0x800
	ds_read_b64_tr_b16 v[134:135], v146 offset:0x1000
	ds_read_b64_tr_b16 v[136:137], v146 offset:0x1800
	ds_read_b64_tr_b16 v[138:139], v146 offset:0x2000
	ds_read_b64_tr_b16 v[140:141], v146 offset:0x2800
	ds_read_b64_tr_b16 v[142:143], v146 offset:0x3000
	ds_read_b64_tr_b16 v[144:145], v146 offset:0x3800
	s_waitcnt lgkmcnt(0)
	s_nop 0
	v_mfma_f32_32x32x16_bf16 v[48:63], v[80:83], v[130:133], v[48:63]
	ds_read_b64_tr_b16 v[130:131], v146 offset:0x200
	ds_read_b64_tr_b16 v[132:133], v146 offset:0xa00
	v_mfma_f32_32x32x16_bf16 v[48:63], v[84:87], v[134:137], v[48:63]
	ds_read_b64_tr_b16 v[134:135], v146 offset:0x1200
	ds_read_b64_tr_b16 v[136:137], v146 offset:0x1a00
	v_mfma_f32_32x32x16_bf16 v[48:63], v[88:91], v[138:141], v[48:63]
	ds_read_b64_tr_b16 v[138:139], v146 offset:0x2200
	ds_read_b64_tr_b16 v[140:141], v146 offset:0x2a00
	v_mfma_f32_32x32x16_bf16 v[48:63], v[92:95], v[142:145], v[48:63]
	ds_read_b64_tr_b16 v[142:143], v146 offset:0x3200
	ds_read_b64_tr_b16 v[144:145], v146 offset:0x3a00
	s_waitcnt lgkmcnt(0)
; #define SBAR() __builtin_amdgcn_sched_barrier(0)
; template <int D0> __device__ __forceinline__ void pv_one(f32x16& od, int vb, bf16x8 pa0, bf16x8 pa1, bf16x8 pa2, bf16x8 pa3) {
;   const s16x4 l0 = tr_read<v_rd_off(D0, 0, 0)>(vb), h0 = tr_read<v_rd_off(D0, 0, 1)>(vb), l1 = tr_read<v_rd_off(D0, 1, 0)>(vb), h1 = tr_read<v_rd_off(D0, 1, 1)>(vb);
;   const s16x4 l2 = tr_read<v_rd_off(D0, 2, 0)>(vb), h2 = tr_read<v_rd_off(D0, 2, 1)>(vb), l3 = tr_read<v_rd_off(D0, 3, 0)>(vb), h3 = tr_read<v_rd_off(D0, 3, 1)>(vb);
;   asm volatile("s_waitcnt lgkmcnt(0)" ::: "memory"); SBAR();
;     ...
;   od = __builtin_amdgcn_mfma_f32_32x32x16_bf16(pa0, PK(l0, h0), od, 0, 0, 0);
;   od = __builtin_amdgcn_mfma_f32_32x32x16_bf16(pa1, PK(l1, h1), od, 0, 0, 0);
;   od = __builtin_amdgcn_mfma_f32_32x32x16_bf16(pa2, PK(l2, h2), od, 0, 0, 0);
;   od = __builtin_amdgcn_mfma_f32_32x32x16_bf16(pa3, PK(l3, h3), od, 0, 0, 0);
;     ...
; }
; __device__ __forceinline__ void pv_d0(f32x16* o, int vb, bf16x8 pa0, bf16x8 pa1, bf16x8 pa2, bf16x8 pa3) {
;   pv_one<0>(o[0], vb, pa0, pa1, pa2, pa3); pv_one<1>(o[1], vb, pa0, pa1, pa2, pa3); pv_one<2>(o[2], vb, pa0, pa1, pa2, pa3); pv_one<3>(o[3], vb, pa0, pa1, pa2, pa3);
; template <typename TQ>
; __device__ __forceinline__ void attn_dense_body(const TQ* __restrict__ Qb, const bf16* __restrict__ Kh, const bf16* __restrict__ Vh,
;                                                 bf16* __restrict__ Ob, int seq, char* lds, float mraw) {
;     ...
;   pv_d0(o, VBUF(bprev), pa0, pa1, pa2, pa3); partialSM_fixed(pB0, pB1, mnC);
;   finishSM(pB0, pB1, 1.f, lacc, pa0, pa1, pa2, pa3); SBAR();
;   pv_d0(o, VBUF(bcur), pa0, pa1, pa2, pa3);
	v_mfma_f32_32x32x16_bf16 v[64:79], v[80:83], v[130:133], v[64:79]
	ds_read_b64_tr_b16 v[130:131], v146 offset:0x400
	ds_read_b64_tr_b16 v[132:133], v146 offset:0xc00
	v_mfma_f32_32x32x16_bf16 v[64:79], v[84:87], v[134:137], v[64:79]
	ds_read_b64_tr_b16 v[134:135], v146 offset:0x1400
	ds_read_b64_tr_b16 v[136:137], v146 offset:0x1c00
	v_mfma_f32_32x32x16_bf16 v[64:79], v[88:91], v[138:141], v[64:79]
	ds_read_b64_tr_b16 v[138:139], v146 offset:0x2400
	ds_read_b64_tr_b16 v[140:141], v146 offset:0x2c00
	v_mfma_f32_32x32x16_bf16 v[64:79], v[92:95], v[142:145], v[64:79]
	ds_read_b64_tr_b16 v[142:143], v146 offset:0x3400
	ds_read_b64_tr_b16 v[144:145], v146 offset:0x3c00
	s_waitcnt lgkmcnt(0)
	v_mfma_f32_32x32x16_bf16 v[32:47], v[80:83], v[130:133], v[32:47]
	ds_read_b64_tr_b16 v[130:131], v146 offset:0x600
	ds_read_b64_tr_b16 v[132:133], v146 offset:0xe00
	v_mfma_f32_32x32x16_bf16 v[32:47], v[84:87], v[134:137], v[32:47]
	ds_read_b64_tr_b16 v[134:135], v146 offset:0x1600
	ds_read_b64_tr_b16 v[136:137], v146 offset:0x1e00
	v_mfma_f32_32x32x16_bf16 v[32:47], v[88:91], v[138:141], v[32:47]
	ds_read_b64_tr_b16 v[138:139], v146 offset:0x2600
	ds_read_b64_tr_b16 v[140:141], v146 offset:0x2e00
	v_mfma_f32_32x32x16_bf16 v[32:47], v[92:95], v[142:145], v[32:47]
	ds_read_b64_tr_b16 v[142:143], v146 offset:0x3600
	ds_read_b64_tr_b16 v[144:145], v146 offset:0x3e00
	s_waitcnt lgkmcnt(0)
	v_mfma_f32_32x32x16_bf16 v[16:31], v[80:83], v[130:133], v[16:31]
	v_exp_f32_e32 v80, v112
	v_exp_f32_e32 v81, v113
	v_exp_f32_e32 v82, v114
	v_exp_f32_e32 v83, v115
	v_exp_f32_e32 v112, v126
	v_exp_f32_e32 v113, v127
	v_exp_f32_e32 v96, v96
	v_mfma_f32_32x32x16_bf16 v[16:31], v[84:87], v[134:137], v[16:31]
	v_exp_f32_e32 v86, v116
	v_exp_f32_e32 v87, v117
	v_cvt_pk_bf16_f32 v84, v80, v81
	v_cvt_pk_bf16_f32 v85, v82, v83
	v_exp_f32_e32 v97, v97
	v_exp_f32_e32 v98, v98
	v_exp_f32_e32 v99, v99
	v_mfma_f32_32x32x16_bf16 v[16:31], v[88:91], v[138:141], v[16:31]
	v_exp_f32_e32 v88, v118
	v_exp_f32_e32 v89, v119
	v_exp_f32_e32 v90, v120
	v_exp_f32_e32 v91, v121
	s_nop 1
	v_add_f32 v194, v194, v80
	v_add_f32 v195, v195, v81
	v_add_f32 v196, v196, v82
	v_add_f32 v197, v197, v83
	v_add_f32 v198, v198, v86
	v_add_f32 v187, v187, v87
	v_add_f32 v188, v188, v88
	v_add_f32 v189, v189, v89
	v_cvt_pk_bf16_f32 v86, v86, v87
	v_cvt_pk_bf16_f32 v87, v88, v89
	v_mfma_f32_32x32x16_bf16 v[16:31], v[92:95], v[142:145], v[16:31]
	v_exp_f32_e32 v92, v122
	v_exp_f32_e32 v93, v123
	v_exp_f32_e32 v94, v124
	v_exp_f32_e32 v95, v125
	v_cvt_pk_bf16_f32 v80, v90, v91
	v_cvt_pk_bf16_f32 v81, v92, v93
	v_cvt_pk_bf16_f32 v82, v94, v95
	v_cvt_pk_bf16_f32 v83, v112, v113
	v_exp_f32_e32 v100, v100
	v_exp_f32_e32 v101, v101
	v_exp_f32_e32 v102, v102
	v_exp_f32_e32 v103, v103
	v_exp_f32_e32 v104, v104
	v_exp_f32_e32 v105, v105
	v_exp_f32_e32 v106, v106
	v_exp_f32_e32 v107, v107
	v_exp_f32_e32 v108, v108
	v_exp_f32_e32 v109, v109
	v_exp_f32_e32 v110, v110
	v_exp_f32_e32 v111, v111
	s_nop 1
	v_add_f32 v190, v190, v90
	v_add_f32 v191, v191, v91
	v_add_f32 v192, v192, v92
	v_add_f32 v193, v193, v93
	v_add_f32 v183, v183, v94
	v_add_f32 v184, v184, v95
	v_add_f32 v185, v185, v112
	v_add_f32 v186, v186, v113
	v_permlane32_swap_b32_e32 v80, v82
	v_permlane32_swap_b32_e32 v81, v83
	v_cvt_pk_bf16_f32 v88, v96, v97
	v_cvt_pk_bf16_f32 v89, v98, v99
	v_cvt_pk_bf16_f32 v90, v100, v101
	v_cvt_pk_bf16_f32 v91, v102, v103
	v_cvt_pk_bf16_f32 v92, v104, v105
	v_cvt_pk_bf16_f32 v93, v106, v107
	v_cvt_pk_bf16_f32 v94, v108, v109
	v_cvt_pk_bf16_f32 v95, v110, v111
	s_nop 1
	v_add_f32 v194, v194, v96
	v_add_f32 v195, v195, v97
	v_add_f32 v196, v196, v98
	v_add_f32 v197, v197, v99
	v_add_f32 v198, v198, v100
	v_add_f32 v187, v187, v101
	v_add_f32 v188, v188, v102
	v_add_f32 v189, v189, v103
	s_nop 1
	v_add_f32 v190, v190, v104
	v_add_f32 v191, v191, v105
	v_add_f32 v192, v192, v106
	v_add_f32 v193, v193, v107
	v_add_f32 v183, v183, v108
	v_add_f32 v184, v184, v109
	v_add_f32 v185, v185, v110
	v_add_f32 v186, v186, v111
	v_permlane32_swap_b32_e32 v84, v86
	v_permlane32_swap_b32_e32 v85, v87
	v_permlane32_swap_b32_e32 v88, v90
	v_permlane32_swap_b32_e32 v89, v91
	v_permlane32_swap_b32_e32 v92, v94
	v_permlane32_swap_b32_e32 v93, v95
	ds_read_b64_tr_b16 v[96:97], v201 offset:0
	ds_read_b64_tr_b16 v[98:99], v201 offset:0x800
	ds_read_b64_tr_b16 v[100:101], v201 offset:0x1000
	ds_read_b64_tr_b16 v[102:103], v201 offset:0x1800
	ds_read_b64_tr_b16 v[104:105], v201 offset:0x2000
	ds_read_b64_tr_b16 v[106:107], v201 offset:0x2800
	ds_read_b64_tr_b16 v[108:109], v201 offset:0x3000
	ds_read_b64_tr_b16 v[110:111], v201 offset:0x3800
	s_waitcnt lgkmcnt(0)
	s_nop 0
	v_mfma_f32_32x32x16_bf16 v[48:63], v[84:87], v[96:99], v[48:63]
	ds_read_b64_tr_b16 v[96:97], v201 offset:0x200
	ds_read_b64_tr_b16 v[98:99], v201 offset:0xa00
	v_mfma_f32_32x32x16_bf16 v[48:63], v[80:83], v[100:103], v[48:63]
	ds_read_b64_tr_b16 v[100:101], v201 offset:0x1200
	ds_read_b64_tr_b16 v[102:103], v201 offset:0x1a00
	v_mfma_f32_32x32x16_bf16 v[48:63], v[88:91], v[104:107], v[48:63]
	ds_read_b64_tr_b16 v[104:105], v201 offset:0x2200
	ds_read_b64_tr_b16 v[106:107], v201 offset:0x2a00
	v_mfma_f32_32x32x16_bf16 v[48:63], v[92:95], v[108:111], v[48:63]
	ds_read_b64_tr_b16 v[108:109], v201 offset:0x3200
	ds_read_b64_tr_b16 v[110:111], v201 offset:0x3a00
	s_waitcnt lgkmcnt(0)
; __device__ __forceinline__ int crow(int r, int hi) { return (r & 3) + 8 * (r >> 2) + 4 * hi; }
; template <typename TQ>
; __device__ __forceinline__ void attn_dense_body(const TQ* __restrict__ Qb, const bf16* __restrict__ Kh, const bf16* __restrict__ Vh,
;                                                 bf16* __restrict__ Ob, int seq, char* lds, float mraw) {
;     ...
;   float l_reg = 0; for (int r = 0; r < 16; ++r) l_reg += lacc[r];
;   { auto rr = __builtin_amdgcn_permlane32_swap(__float_as_uint(l_reg), __float_as_uint(l_reg), false, false); l_reg = __uint_as_float(rr[0]) + __uint_as_float(rr[1]); }
;   if (hi == 0) li_l[r32] = l_reg; asm volatile("s_waitcnt lgkmcnt(0)" ::: "memory");
;   float rli[16];
; #pragma unroll
;   for (int r = 0; r < 16; ++r) rli[r] = __builtin_amdgcn_rcpf(li_l[crow(r, hi)]);
;   bf16* Ow = Ob + (long)(wid * QBLK) * LDO;
; #pragma unroll
;   for (int r = 0; r < 16; ++r) { int orow = crow(r, hi);
; #pragma unroll
;     for (int d0 = 0; d0 < 4; ++d0) { const float v = o[d0][r] * rli[r]; const float nb = __shfl_xor(v, 1);
;       if (!(r32 & 1)) *reinterpret_cast<unsigned*>(Ow + (long)orow * LDO + d0 * 32 + r32) = cvtpk(v, nb); } }
	v_mfma_f32_32x32x16_bf16 v[64:79], v[84:87], v[96:99], v[64:79]
	ds_read_b64_tr_b16 v[96:97], v201 offset:0x400
	ds_read_b64_tr_b16 v[98:99], v201 offset:0xc00
	v_mfma_f32_32x32x16_bf16 v[64:79], v[80:83], v[100:103], v[64:79]
	ds_read_b64_tr_b16 v[100:101], v201 offset:0x1400
	ds_read_b64_tr_b16 v[102:103], v201 offset:0x1c00
	v_mfma_f32_32x32x16_bf16 v[64:79], v[88:91], v[104:107], v[64:79]
	ds_read_b64_tr_b16 v[104:105], v201 offset:0x2400
	ds_read_b64_tr_b16 v[106:107], v201 offset:0x2c00
	v_mfma_f32_32x32x16_bf16 v[64:79], v[92:95], v[108:111], v[64:79]
	ds_read_b64_tr_b16 v[108:109], v201 offset:0x3400
	ds_read_b64_tr_b16 v[110:111], v201 offset:0x3c00
	s_waitcnt lgkmcnt(0)
	v_mfma_f32_32x32x16_bf16 v[32:47], v[84:87], v[96:99], v[32:47]
	ds_read_b64_tr_b16 v[96:97], v201 offset:0x600
	ds_read_b64_tr_b16 v[98:99], v201 offset:0xe00
	v_mfma_f32_32x32x16_bf16 v[32:47], v[80:83], v[100:103], v[32:47]
	ds_read_b64_tr_b16 v[100:101], v201 offset:0x1600
	ds_read_b64_tr_b16 v[102:103], v201 offset:0x1e00
	v_mfma_f32_32x32x16_bf16 v[32:47], v[88:91], v[104:107], v[32:47]
	ds_read_b64_tr_b16 v[104:105], v201 offset:0x2600
	ds_read_b64_tr_b16 v[106:107], v201 offset:0x2e00
	v_mfma_f32_32x32x16_bf16 v[32:47], v[92:95], v[108:111], v[32:47]
	ds_read_b64_tr_b16 v[108:109], v201 offset:0x3600
	ds_read_b64_tr_b16 v[110:111], v201 offset:0x3e00
	s_waitcnt lgkmcnt(0)
	v_mfma_f32_32x32x16_bf16 v[16:31], v[84:87], v[96:99], v[16:31]
	v_add_f32_e32 v84, 0, v194
	v_add_f32_e32 v84, v195, v84
	v_add_f32_e32 v84, v196, v84
	v_add_f32_e32 v84, v197, v84
	v_add_f32_e32 v84, v198, v84
	v_cmp_gt_u32_e32 vcc, 32, v182
	v_mfma_f32_32x32x16_bf16 v[16:31], v[80:83], v[100:103], v[16:31]
	v_add_f32_e32 v80, v187, v84
	v_add_f32_e32 v80, v188, v80
	v_add_f32_e32 v80, v189, v80
	v_add_f32_e32 v80, v190, v80
	v_add_f32_e32 v80, v191, v80
	v_add_f32_e32 v80, v192, v80
	v_add_f32_e32 v80, v193, v80
	v_mfma_f32_32x32x16_bf16 v[16:31], v[88:91], v[104:107], v[16:31]
	v_add_f32_e32 v80, v183, v80
	v_add_f32_e32 v80, v184, v80
	v_add_f32_e32 v80, v185, v80
	v_add_f32_e32 v80, v186, v80
	v_mov_b32_e32 v81, v80
	s_nop 1
	v_permlane32_swap_b32_e32 v80, v81
	v_mfma_f32_32x32x16_bf16 v[16:31], v[92:95], v[108:111], v[16:31]
	s_and_saveexec_b64 s[52:53], vcc
	v_lshl_add_u32 v82, v180, 2, s11
	v_add_f32_e32 v80, v80, v81
	ds_write_b32 v82, v80
	s_or_b64 exec, exec, s[52:53]
	s_waitcnt lgkmcnt(0)
	v_add_u32_e32 v80, s11, v128
	s_lshl_b64 s[6:7], s[6:7], 11
	ds_read_b128 v[92:95], v80
	ds_read_b128 v[88:91], v80 offset:32
	s_add_u32 s6, s3, s6
	s_addc_u32 s7, s13, s7
	s_add_u32 s12, s6, s20
	s_addc_u32 s17, s7, s21
	s_waitcnt lgkmcnt(0)
	v_rcp_f32_e32 v92, v92
	s_ashr_i32 s19, s18, 31
	s_lshl_b64 s[6:7], s[18:19], 11
	s_add_u32 s16, s12, s6
	s_addc_u32 s17, s17, s7
	v_and_b32_e32 v96, 1, v179
	v_lshlrev_b32_e32 v128, 1, v180
	v_cmp_eq_u32_e64 s[6:7], 0, v96
	v_lshlrev_b32_e32 v96, 13, v181
	v_lshl_add_u64 v[98:99], s[16:17], 0, v[128:129]
	v_mov_b32_e32 v97, v129
	v_mul_f32_e32 v48, v48, v92
	ds_read_b128 v[84:87], v80 offset:64
	ds_read_b128 v[80:83], v80 offset:96
	v_lshl_add_u64 v[96:97], v[98:99], 0, v[96:97]
	s_nop 1
	v_mov_b32_dpp v98, v48 quad_perm:[1,0,3,2] row_mask:0xf bank_mask:0xf
	s_and_saveexec_b64 s[18:19], s[6:7]
	v_readlane_b32 s26, v254, 35
	v_readlane_b32 s28, v254, 34
	v_readlane_b32 s27, v254, 36
	v_readlane_b32 s23, v255, 19
	s_cbranch_execz .LBB0_621
	s_waitcnt lgkmcnt(0)
	v_cvt_pk_bf16_f32 v48, v48, v98
	global_store_dword v[96:97], v48, off
.LBB0_621:
	s_or_b64 exec, exec, s[18:19]
	v_mul_f32_e32 v48, v64, v92
	s_nop 1
	v_mov_b32_dpp v64, v48 quad_perm:[1,0,3,2] row_mask:0xf bank_mask:0xf
	s_and_saveexec_b64 s[18:19], s[6:7]
	s_cbranch_execz .LBB0_623
	s_waitcnt lgkmcnt(0)
	v_cvt_pk_bf16_f32 v48, v48, v64
	global_store_dword v[96:97], v48, off offset:64
.LBB0_623:
	s_or_b64 exec, exec, s[18:19]
	v_mul_f32_e32 v32, v32, v92
	s_nop 1
	v_mov_b32_dpp v48, v32 quad_perm:[1,0,3,2] row_mask:0xf bank_mask:0xf
	s_and_saveexec_b64 s[18:19], s[6:7]
	s_cbranch_execz .LBB0_625
	s_waitcnt lgkmcnt(0)
	v_cvt_pk_bf16_f32 v32, v32, v48
	global_store_dword v[96:97], v32, off offset:128
.LBB0_625:
	s_or_b64 exec, exec, s[18:19]
	v_mul_f32_e32 v16, v16, v92
	s_nop 1
	v_mov_b32_dpp v32, v16 quad_perm:[1,0,3,2] row_mask:0xf bank_mask:0xf
	s_and_saveexec_b64 s[18:19], s[6:7]
	s_cbranch_execz .LBB0_627
	s_waitcnt lgkmcnt(0)
	v_cvt_pk_bf16_f32 v16, v16, v32
	global_store_dword v[96:97], v16, off offset:192
.LBB0_627:
	s_or_b64 exec, exec, s[18:19]
	v_rcp_f32_e32 v16, v93
	s_waitcnt lgkmcnt(0)
	v_mul_f32_e32 v32, v49, v16
	s_nop 1
	v_mov_b32_dpp v48, v32 quad_perm:[1,0,3,2] row_mask:0xf bank_mask:0xf
	s_and_saveexec_b64 s[18:19], s[6:7]
	s_cbranch_execz .LBB0_629
	s_waitcnt lgkmcnt(0)
	v_cvt_pk_bf16_f32 v32, v32, v48
	global_store_dword v[96:97], v32, off offset:2048
.LBB0_629:
	s_or_b64 exec, exec, s[18:19]
	v_mul_f32_e32 v32, v65, v16
	s_waitcnt lgkmcnt(0)
	s_nop 1
	v_mov_b32_dpp v48, v32 quad_perm:[1,0,3,2] row_mask:0xf bank_mask:0xf
	s_and_saveexec_b64 s[18:19], s[6:7]
	s_cbranch_execz .LBB0_631
	s_waitcnt lgkmcnt(0)
	v_cvt_pk_bf16_f32 v32, v32, v48
	global_store_dword v[96:97], v32, off offset:2112
.LBB0_631:
	s_or_b64 exec, exec, s[18:19]
	v_mul_f32_e32 v32, v33, v16
	s_nop 1
	v_mov_b32_dpp v33, v32 quad_perm:[1,0,3,2] row_mask:0xf bank_mask:0xf
	s_and_saveexec_b64 s[18:19], s[6:7]
	s_cbranch_execz .LBB0_633
	s_waitcnt lgkmcnt(0)
	v_cvt_pk_bf16_f32 v32, v32, v33
	global_store_dword v[96:97], v32, off offset:2176
.LBB0_633:
	s_or_b64 exec, exec, s[18:19]
	v_mul_f32_e32 v16, v17, v16
	s_nop 1
	v_mov_b32_dpp v17, v16 quad_perm:[1,0,3,2] row_mask:0xf bank_mask:0xf
	s_and_saveexec_b64 s[18:19], s[6:7]
	s_cbranch_execz .LBB0_635
	s_waitcnt lgkmcnt(0)
	v_cvt_pk_bf16_f32 v16, v16, v17
	global_store_dword v[96:97], v16, off offset:2240
; __device__ __forceinline__ int crow(int r, int hi) { return (r & 3) + 8 * (r >> 2) + 4 * hi; }
; template <typename TQ>
; __device__ __forceinline__ void attn_dense_body(const TQ* __restrict__ Qb, const bf16* __restrict__ Kh, const bf16* __restrict__ Vh,
;                                                 bf16* __restrict__ Ob, int seq, char* lds, float mraw) {
;     ...
;   for (int r = 0; r < 16; ++r) { int orow = crow(r, hi);
; #pragma unroll
;     for (int d0 = 0; d0 < 4; ++d0) { const float v = o[d0][r] * rli[r]; const float nb = __shfl_xor(v, 1);
;       if (!(r32 & 1)) *reinterpret_cast<unsigned*>(Ow + (long)orow * LDO + d0 * 32 + r32) = cvtpk(v, nb); } }
.LBB0_635:
	s_or_b64 exec, exec, s[18:19]
	v_rcp_f32_e32 v16, v94
	s_waitcnt lgkmcnt(0)
	v_mul_f32_e32 v17, v50, v16
	s_nop 1
	v_mov_b32_dpp v32, v17 quad_perm:[1,0,3,2] row_mask:0xf bank_mask:0xf
	s_and_saveexec_b64 s[18:19], s[6:7]
	s_cbranch_execz .LBB0_637
	s_waitcnt lgkmcnt(0)
	v_cvt_pk_bf16_f32 v17, v17, v32
	v_add_co_u32_e32 v32, vcc, 0x1000, v96
	s_nop 1
	v_addc_co_u32_e32 v33, vcc, 0, v97, vcc
	global_store_dword v[32:33], v17, off
.LBB0_637:
	s_or_b64 exec, exec, s[18:19]
	v_mul_f32_e32 v17, v66, v16
	s_waitcnt lgkmcnt(0)
	s_nop 1
	v_mov_b32_dpp v32, v17 quad_perm:[1,0,3,2] row_mask:0xf bank_mask:0xf
	s_and_saveexec_b64 s[18:19], s[6:7]
	s_cbranch_execz .LBB0_639
	s_waitcnt lgkmcnt(0)
	v_cvt_pk_bf16_f32 v17, v17, v32
	v_add_co_u32_e32 v32, vcc, 0x1000, v96
	s_nop 1
	v_addc_co_u32_e32 v33, vcc, 0, v97, vcc
	global_store_dword v[32:33], v17, off offset:64
.LBB0_639:
	s_or_b64 exec, exec, s[18:19]
	v_mul_f32_e32 v17, v34, v16
	s_waitcnt lgkmcnt(0)
	s_nop 1
	v_mov_b32_dpp v32, v17 quad_perm:[1,0,3,2] row_mask:0xf bank_mask:0xf
	s_and_saveexec_b64 s[18:19], s[6:7]
	s_cbranch_execz .LBB0_641
	s_waitcnt lgkmcnt(0)
	v_cvt_pk_bf16_f32 v17, v17, v32
	v_add_co_u32_e32 v32, vcc, 0x1000, v96
	s_nop 1
	v_addc_co_u32_e32 v33, vcc, 0, v97, vcc
	global_store_dword v[32:33], v17, off offset:128
.LBB0_641:
	s_or_b64 exec, exec, s[18:19]
	v_mul_f32_e32 v16, v18, v16
	s_nop 1
	v_mov_b32_dpp v17, v16 quad_perm:[1,0,3,2] row_mask:0xf bank_mask:0xf
	s_and_saveexec_b64 s[18:19], s[6:7]
	s_cbranch_execz .LBB0_643
	s_waitcnt lgkmcnt(0)
	v_cvt_pk_bf16_f32 v18, v16, v17
	v_add_co_u32_e32 v16, vcc, 0x1000, v96
	s_nop 1
	v_addc_co_u32_e32 v17, vcc, 0, v97, vcc
	global_store_dword v[16:17], v18, off offset:192
.LBB0_643:
	s_or_b64 exec, exec, s[18:19]
	v_rcp_f32_e32 v16, v95
	s_waitcnt lgkmcnt(0)
	v_mul_f32_e32 v17, v51, v16
	s_nop 1
	v_mov_b32_dpp v18, v17 quad_perm:[1,0,3,2] row_mask:0xf bank_mask:0xf
	s_and_saveexec_b64 s[18:19], s[6:7]
	s_cbranch_execz .LBB0_645
	v_add_co_u32_e32 v32, vcc, 0x1000, v96
	s_waitcnt lgkmcnt(0)
	v_cvt_pk_bf16_f32 v17, v17, v18
	s_nop 0
	v_addc_co_u32_e32 v33, vcc, 0, v97, vcc
	global_store_dword v[32:33], v17, off offset:2048
.LBB0_645:
	s_or_b64 exec, exec, s[18:19]
	v_mul_f32_e32 v17, v67, v16
	s_waitcnt lgkmcnt(0)
	s_nop 1
	v_mov_b32_dpp v18, v17 quad_perm:[1,0,3,2] row_mask:0xf bank_mask:0xf
	s_and_saveexec_b64 s[18:19], s[6:7]
	s_cbranch_execz .LBB0_647
	v_add_co_u32_e32 v32, vcc, 0x1000, v96
	s_waitcnt lgkmcnt(0)
	v_cvt_pk_bf16_f32 v17, v17, v18
	s_nop 0
	v_addc_co_u32_e32 v33, vcc, 0, v97, vcc
	global_store_dword v[32:33], v17, off offset:2112
.LBB0_647:
	s_or_b64 exec, exec, s[18:19]
	v_mul_f32_e32 v17, v35, v16
	s_waitcnt lgkmcnt(0)
	s_nop 1
	v_mov_b32_dpp v18, v17 quad_perm:[1,0,3,2] row_mask:0xf bank_mask:0xf
	s_and_saveexec_b64 s[18:19], s[6:7]
	s_cbranch_execz .LBB0_649
	v_add_co_u32_e32 v32, vcc, 0x1000, v96
	s_waitcnt lgkmcnt(0)
	v_cvt_pk_bf16_f32 v17, v17, v18
	s_nop 0
	v_addc_co_u32_e32 v33, vcc, 0, v97, vcc
	global_store_dword v[32:33], v17, off offset:2176
.LBB0_649:
	s_or_b64 exec, exec, s[18:19]
	v_mul_f32_e32 v16, v19, v16
	s_nop 1
	v_mov_b32_dpp v17, v16 quad_perm:[1,0,3,2] row_mask:0xf bank_mask:0xf
	s_and_saveexec_b64 s[18:19], s[6:7]
	s_cbranch_execz .LBB0_651
	s_waitcnt lgkmcnt(0)
	v_cvt_pk_bf16_f32 v18, v16, v17
	v_add_co_u32_e32 v16, vcc, 0x1000, v96
	s_nop 1
	v_addc_co_u32_e32 v17, vcc, 0, v97, vcc
	global_store_dword v[16:17], v18, off offset:2240
.LBB0_651:
	s_or_b64 exec, exec, s[18:19]
	v_rcp_f32_e32 v16, v88
	s_waitcnt lgkmcnt(0)
	v_mul_f32_e32 v17, v52, v16
	s_nop 1
	v_mov_b32_dpp v18, v17 quad_perm:[1,0,3,2] row_mask:0xf bank_mask:0xf
	s_and_saveexec_b64 s[18:19], s[6:7]
	s_cbranch_execz .LBB0_653
	s_waitcnt lgkmcnt(0)
	v_cvt_pk_bf16_f32 v17, v17, v18
	v_add_co_u32_e32 v18, vcc, 0x4000, v96
	s_nop 1
	v_addc_co_u32_e32 v19, vcc, 0, v97, vcc
	global_store_dword v[18:19], v17, off
.LBB0_653:
	s_or_b64 exec, exec, s[18:19]
	v_mul_f32_e32 v17, v68, v16
	s_waitcnt lgkmcnt(0)
	s_nop 1
	v_mov_b32_dpp v18, v17 quad_perm:[1,0,3,2] row_mask:0xf bank_mask:0xf
	s_and_saveexec_b64 s[18:19], s[6:7]
	s_cbranch_execz .LBB0_655
	s_waitcnt lgkmcnt(0)
	v_cvt_pk_bf16_f32 v17, v17, v18
	v_add_co_u32_e32 v18, vcc, 0x4000, v96
	s_nop 1
	v_addc_co_u32_e32 v19, vcc, 0, v97, vcc
	global_store_dword v[18:19], v17, off offset:64
.LBB0_655:
	s_or_b64 exec, exec, s[18:19]
	v_mul_f32_e32 v17, v36, v16
	s_waitcnt lgkmcnt(0)
	s_nop 1
	v_mov_b32_dpp v18, v17 quad_perm:[1,0,3,2] row_mask:0xf bank_mask:0xf
	s_and_saveexec_b64 s[18:19], s[6:7]
	s_cbranch_execz .LBB0_657
	s_waitcnt lgkmcnt(0)
	v_cvt_pk_bf16_f32 v17, v17, v18
	v_add_co_u32_e32 v18, vcc, 0x4000, v96
	s_nop 1
	v_addc_co_u32_e32 v19, vcc, 0, v97, vcc
	global_store_dword v[18:19], v17, off offset:128
.LBB0_657:
	s_or_b64 exec, exec, s[18:19]
	v_mul_f32_e32 v16, v20, v16
	s_nop 1
	v_mov_b32_dpp v17, v16 quad_perm:[1,0,3,2] row_mask:0xf bank_mask:0xf
	s_and_saveexec_b64 s[18:19], s[6:7]
	s_cbranch_execz .LBB0_659
	s_waitcnt lgkmcnt(0)
	v_cvt_pk_bf16_f32 v18, v16, v17
	v_add_co_u32_e32 v16, vcc, 0x4000, v96
	s_nop 1
	v_addc_co_u32_e32 v17, vcc, 0, v97, vcc
	global_store_dword v[16:17], v18, off offset:192
.LBB0_659:
	s_or_b64 exec, exec, s[18:19]
	v_rcp_f32_e32 v16, v89
	s_waitcnt lgkmcnt(0)
	v_mul_f32_e32 v17, v53, v16
	s_nop 1
	v_mov_b32_dpp v18, v17 quad_perm:[1,0,3,2] row_mask:0xf bank_mask:0xf
	s_and_saveexec_b64 s[18:19], s[6:7]
	s_cbranch_execz .LBB0_661
	s_waitcnt lgkmcnt(0)
	v_cvt_pk_bf16_f32 v17, v17, v18
	v_add_co_u32_e32 v18, vcc, 0x4000, v96
	s_nop 1
	v_addc_co_u32_e32 v19, vcc, 0, v97, vcc
	global_store_dword v[18:19], v17, off offset:2048
; __device__ __forceinline__ int crow(int r, int hi) { return (r & 3) + 8 * (r >> 2) + 4 * hi; }
; template <typename TQ>
; __device__ __forceinline__ void attn_dense_body(const TQ* __restrict__ Qb, const bf16* __restrict__ Kh, const bf16* __restrict__ Vh,
;                                                 bf16* __restrict__ Ob, int seq, char* lds, float mraw) {
;     ...
;   for (int r = 0; r < 16; ++r) { int orow = crow(r, hi);
; #pragma unroll
;     for (int d0 = 0; d0 < 4; ++d0) { const float v = o[d0][r] * rli[r]; const float nb = __shfl_xor(v, 1);
;       if (!(r32 & 1)) *reinterpret_cast<unsigned*>(Ow + (long)orow * LDO + d0 * 32 + r32) = cvtpk(v, nb); } }
.LBB0_661:
	s_or_b64 exec, exec, s[18:19]
	v_mul_f32_e32 v17, v69, v16
	s_waitcnt lgkmcnt(0)
	s_nop 1
	v_mov_b32_dpp v18, v17 quad_perm:[1,0,3,2] row_mask:0xf bank_mask:0xf
	s_and_saveexec_b64 s[18:19], s[6:7]
	s_cbranch_execz .LBB0_663
	s_waitcnt lgkmcnt(0)
	v_cvt_pk_bf16_f32 v17, v17, v18
	v_add_co_u32_e32 v18, vcc, 0x4000, v96
	s_nop 1
	v_addc_co_u32_e32 v19, vcc, 0, v97, vcc
	global_store_dword v[18:19], v17, off offset:2112
.LBB0_663:
	s_or_b64 exec, exec, s[18:19]
	v_mul_f32_e32 v17, v37, v16
	s_waitcnt lgkmcnt(0)
	s_nop 1
	v_mov_b32_dpp v18, v17 quad_perm:[1,0,3,2] row_mask:0xf bank_mask:0xf
	s_and_saveexec_b64 s[18:19], s[6:7]
	s_cbranch_execz .LBB0_665
	s_waitcnt lgkmcnt(0)
	v_cvt_pk_bf16_f32 v17, v17, v18
	v_add_co_u32_e32 v18, vcc, 0x4000, v96
	s_nop 1
	v_addc_co_u32_e32 v19, vcc, 0, v97, vcc
	global_store_dword v[18:19], v17, off offset:2176
.LBB0_665:
	s_or_b64 exec, exec, s[18:19]
	v_mul_f32_e32 v16, v21, v16
	s_nop 1
	v_mov_b32_dpp v17, v16 quad_perm:[1,0,3,2] row_mask:0xf bank_mask:0xf
	s_and_saveexec_b64 s[18:19], s[6:7]
	s_cbranch_execz .LBB0_667
	s_waitcnt lgkmcnt(0)
	v_cvt_pk_bf16_f32 v18, v16, v17
	v_add_co_u32_e32 v16, vcc, 0x4000, v96
	s_nop 1
	v_addc_co_u32_e32 v17, vcc, 0, v97, vcc
	global_store_dword v[16:17], v18, off offset:2240
.LBB0_667:
	s_or_b64 exec, exec, s[18:19]
	v_rcp_f32_e32 v16, v90
	s_waitcnt lgkmcnt(0)
	v_mul_f32_e32 v17, v54, v16
	s_nop 1
	v_mov_b32_dpp v18, v17 quad_perm:[1,0,3,2] row_mask:0xf bank_mask:0xf
	s_and_saveexec_b64 s[18:19], s[6:7]
	s_cbranch_execz .LBB0_669
	s_waitcnt lgkmcnt(0)
	v_cvt_pk_bf16_f32 v17, v17, v18
	v_add_co_u32_e32 v18, vcc, 0x5000, v96
	s_nop 1
	v_addc_co_u32_e32 v19, vcc, 0, v97, vcc
	global_store_dword v[18:19], v17, off
.LBB0_669:
	s_or_b64 exec, exec, s[18:19]
	v_mul_f32_e32 v17, v70, v16
	s_waitcnt lgkmcnt(0)
	s_nop 1
	v_mov_b32_dpp v18, v17 quad_perm:[1,0,3,2] row_mask:0xf bank_mask:0xf
	s_and_saveexec_b64 s[18:19], s[6:7]
	s_cbranch_execz .LBB0_671
	s_waitcnt lgkmcnt(0)
	v_cvt_pk_bf16_f32 v17, v17, v18
	v_add_co_u32_e32 v18, vcc, 0x5000, v96
	s_nop 1
	v_addc_co_u32_e32 v19, vcc, 0, v97, vcc
	global_store_dword v[18:19], v17, off offset:64
.LBB0_671:
	s_or_b64 exec, exec, s[18:19]
	v_mul_f32_e32 v17, v38, v16
	s_waitcnt lgkmcnt(0)
	s_nop 1
	v_mov_b32_dpp v18, v17 quad_perm:[1,0,3,2] row_mask:0xf bank_mask:0xf
	s_and_saveexec_b64 s[18:19], s[6:7]
	s_cbranch_execz .LBB0_673
	s_waitcnt lgkmcnt(0)
	v_cvt_pk_bf16_f32 v17, v17, v18
	v_add_co_u32_e32 v18, vcc, 0x5000, v96
	s_nop 1
	v_addc_co_u32_e32 v19, vcc, 0, v97, vcc
	global_store_dword v[18:19], v17, off offset:128
.LBB0_673:
	s_or_b64 exec, exec, s[18:19]
	v_mul_f32_e32 v16, v22, v16
	s_nop 1
	v_mov_b32_dpp v17, v16 quad_perm:[1,0,3,2] row_mask:0xf bank_mask:0xf
	s_and_saveexec_b64 s[18:19], s[6:7]
	s_cbranch_execz .LBB0_675
	s_waitcnt lgkmcnt(0)
	v_cvt_pk_bf16_f32 v18, v16, v17
	v_add_co_u32_e32 v16, vcc, 0x5000, v96
	s_nop 1
	v_addc_co_u32_e32 v17, vcc, 0, v97, vcc
	global_store_dword v[16:17], v18, off offset:192
.LBB0_675:
	s_or_b64 exec, exec, s[18:19]
	v_rcp_f32_e32 v16, v91
	s_waitcnt lgkmcnt(0)
	v_mul_f32_e32 v17, v55, v16
	s_nop 1
	v_mov_b32_dpp v18, v17 quad_perm:[1,0,3,2] row_mask:0xf bank_mask:0xf
	s_and_saveexec_b64 s[18:19], s[6:7]
	s_cbranch_execz .LBB0_677
	s_waitcnt lgkmcnt(0)
	v_cvt_pk_bf16_f32 v17, v17, v18
	v_add_co_u32_e32 v18, vcc, 0x5000, v96
	s_nop 1
	v_addc_co_u32_e32 v19, vcc, 0, v97, vcc
	global_store_dword v[18:19], v17, off offset:2048
.LBB0_677:
	s_or_b64 exec, exec, s[18:19]
	v_mul_f32_e32 v17, v71, v16
	s_waitcnt lgkmcnt(0)
	s_nop 1
	v_mov_b32_dpp v18, v17 quad_perm:[1,0,3,2] row_mask:0xf bank_mask:0xf
	s_and_saveexec_b64 s[18:19], s[6:7]
	s_cbranch_execz .LBB0_679
	s_waitcnt lgkmcnt(0)
	v_cvt_pk_bf16_f32 v17, v17, v18
	v_add_co_u32_e32 v18, vcc, 0x5000, v96
	s_nop 1
	v_addc_co_u32_e32 v19, vcc, 0, v97, vcc
	global_store_dword v[18:19], v17, off offset:2112
.LBB0_679:
	s_or_b64 exec, exec, s[18:19]
	v_mul_f32_e32 v17, v39, v16
	s_waitcnt lgkmcnt(0)
	s_nop 1
	v_mov_b32_dpp v18, v17 quad_perm:[1,0,3,2] row_mask:0xf bank_mask:0xf
	s_and_saveexec_b64 s[18:19], s[6:7]
	s_cbranch_execz .LBB0_681
	s_waitcnt lgkmcnt(0)
	v_cvt_pk_bf16_f32 v17, v17, v18
	v_add_co_u32_e32 v18, vcc, 0x5000, v96
	s_nop 1
	v_addc_co_u32_e32 v19, vcc, 0, v97, vcc
	global_store_dword v[18:19], v17, off offset:2176
.LBB0_681:
	s_or_b64 exec, exec, s[18:19]
	v_mul_f32_e32 v16, v23, v16
	s_nop 1
	v_mov_b32_dpp v17, v16 quad_perm:[1,0,3,2] row_mask:0xf bank_mask:0xf
	s_and_saveexec_b64 s[18:19], s[6:7]
	s_cbranch_execz .LBB0_683
	s_waitcnt lgkmcnt(0)
	v_cvt_pk_bf16_f32 v18, v16, v17
	v_add_co_u32_e32 v16, vcc, 0x5000, v96
	s_nop 1
	v_addc_co_u32_e32 v17, vcc, 0, v97, vcc
	global_store_dword v[16:17], v18, off offset:2240
.LBB0_683:
	s_or_b64 exec, exec, s[18:19]
	v_rcp_f32_e32 v16, v84
	s_waitcnt lgkmcnt(0)
	v_mul_f32_e32 v17, v56, v16
	s_nop 1
	v_mov_b32_dpp v18, v17 quad_perm:[1,0,3,2] row_mask:0xf bank_mask:0xf
	s_and_saveexec_b64 s[18:19], s[6:7]
	s_cbranch_execz .LBB0_685
	s_waitcnt lgkmcnt(0)
	v_cvt_pk_bf16_f32 v17, v17, v18
	v_add_co_u32_e32 v18, vcc, 0x8000, v96
	s_nop 1
	v_addc_co_u32_e32 v19, vcc, 0, v97, vcc
	global_store_dword v[18:19], v17, off
.LBB0_685:
	s_or_b64 exec, exec, s[18:19]
	v_mul_f32_e32 v17, v72, v16
	s_waitcnt lgkmcnt(0)
	s_nop 1
	v_mov_b32_dpp v18, v17 quad_perm:[1,0,3,2] row_mask:0xf bank_mask:0xf
	s_and_saveexec_b64 s[18:19], s[6:7]
	s_cbranch_execz .LBB0_687
	s_waitcnt lgkmcnt(0)
	v_cvt_pk_bf16_f32 v17, v17, v18
	v_add_co_u32_e32 v18, vcc, 0x8000, v96
	s_nop 1
	v_addc_co_u32_e32 v19, vcc, 0, v97, vcc
	global_store_dword v[18:19], v17, off offset:64
; __device__ __forceinline__ int crow(int r, int hi) { return (r & 3) + 8 * (r >> 2) + 4 * hi; }
; template <typename TQ>
; __device__ __forceinline__ void attn_dense_body(const TQ* __restrict__ Qb, const bf16* __restrict__ Kh, const bf16* __restrict__ Vh,
;                                                 bf16* __restrict__ Ob, int seq, char* lds, float mraw) {
;     ...
;   for (int r = 0; r < 16; ++r) { int orow = crow(r, hi);
; #pragma unroll
;     for (int d0 = 0; d0 < 4; ++d0) { const float v = o[d0][r] * rli[r]; const float nb = __shfl_xor(v, 1);
;       if (!(r32 & 1)) *reinterpret_cast<unsigned*>(Ow + (long)orow * LDO + d0 * 32 + r32) = cvtpk(v, nb); } }
.LBB0_687:
	s_or_b64 exec, exec, s[18:19]
	v_mul_f32_e32 v17, v40, v16
	s_waitcnt lgkmcnt(0)
	s_nop 1
	v_mov_b32_dpp v18, v17 quad_perm:[1,0,3,2] row_mask:0xf bank_mask:0xf
	s_and_saveexec_b64 s[18:19], s[6:7]
	s_cbranch_execz .LBB0_689
	s_waitcnt lgkmcnt(0)
	v_cvt_pk_bf16_f32 v17, v17, v18
	v_add_co_u32_e32 v18, vcc, 0x8000, v96
	s_nop 1
	v_addc_co_u32_e32 v19, vcc, 0, v97, vcc
	global_store_dword v[18:19], v17, off offset:128
.LBB0_689:
	s_or_b64 exec, exec, s[18:19]
	v_mul_f32_e32 v16, v24, v16
	s_nop 1
	v_mov_b32_dpp v17, v16 quad_perm:[1,0,3,2] row_mask:0xf bank_mask:0xf
	s_and_saveexec_b64 s[18:19], s[6:7]
	s_cbranch_execz .LBB0_691
	s_waitcnt lgkmcnt(0)
	v_cvt_pk_bf16_f32 v18, v16, v17
	v_add_co_u32_e32 v16, vcc, 0x8000, v96
	s_nop 1
	v_addc_co_u32_e32 v17, vcc, 0, v97, vcc
	global_store_dword v[16:17], v18, off offset:192
.LBB0_691:
	s_or_b64 exec, exec, s[18:19]
	v_rcp_f32_e32 v16, v85
	s_waitcnt lgkmcnt(0)
	v_mul_f32_e32 v17, v57, v16
	s_nop 1
	v_mov_b32_dpp v18, v17 quad_perm:[1,0,3,2] row_mask:0xf bank_mask:0xf
	s_and_saveexec_b64 s[18:19], s[6:7]
	s_cbranch_execz .LBB0_693
	s_waitcnt lgkmcnt(0)
	v_cvt_pk_bf16_f32 v17, v17, v18
	v_add_co_u32_e32 v18, vcc, 0x8000, v96
	s_nop 1
	v_addc_co_u32_e32 v19, vcc, 0, v97, vcc
	global_store_dword v[18:19], v17, off offset:2048
.LBB0_693:
	s_or_b64 exec, exec, s[18:19]
	v_mul_f32_e32 v17, v73, v16
	s_waitcnt lgkmcnt(0)
	s_nop 1
	v_mov_b32_dpp v18, v17 quad_perm:[1,0,3,2] row_mask:0xf bank_mask:0xf
	s_and_saveexec_b64 s[18:19], s[6:7]
	s_cbranch_execz .LBB0_695
	s_waitcnt lgkmcnt(0)
	v_cvt_pk_bf16_f32 v17, v17, v18
	v_add_co_u32_e32 v18, vcc, 0x8000, v96
	s_nop 1
	v_addc_co_u32_e32 v19, vcc, 0, v97, vcc
	global_store_dword v[18:19], v17, off offset:2112
.LBB0_695:
	s_or_b64 exec, exec, s[18:19]
	v_mul_f32_e32 v17, v41, v16
	s_waitcnt lgkmcnt(0)
	s_nop 1
	v_mov_b32_dpp v18, v17 quad_perm:[1,0,3,2] row_mask:0xf bank_mask:0xf
	s_and_saveexec_b64 s[18:19], s[6:7]
	s_cbranch_execz .LBB0_697
	s_waitcnt lgkmcnt(0)
	v_cvt_pk_bf16_f32 v17, v17, v18
	v_add_co_u32_e32 v18, vcc, 0x8000, v96
	s_nop 1
	v_addc_co_u32_e32 v19, vcc, 0, v97, vcc
	global_store_dword v[18:19], v17, off offset:2176
.LBB0_697:
	s_or_b64 exec, exec, s[18:19]
	v_mul_f32_e32 v16, v25, v16
	s_nop 1
	v_mov_b32_dpp v17, v16 quad_perm:[1,0,3,2] row_mask:0xf bank_mask:0xf
	s_and_saveexec_b64 s[18:19], s[6:7]
	s_cbranch_execz .LBB0_699
	s_waitcnt lgkmcnt(0)
	v_cvt_pk_bf16_f32 v18, v16, v17
	v_add_co_u32_e32 v16, vcc, 0x8000, v96
	s_nop 1
	v_addc_co_u32_e32 v17, vcc, 0, v97, vcc
	global_store_dword v[16:17], v18, off offset:2240
.LBB0_699:
	s_or_b64 exec, exec, s[18:19]
	v_rcp_f32_e32 v16, v86
	s_waitcnt lgkmcnt(0)
	v_mul_f32_e32 v17, v58, v16
	s_nop 1
	v_mov_b32_dpp v18, v17 quad_perm:[1,0,3,2] row_mask:0xf bank_mask:0xf
	s_and_saveexec_b64 s[18:19], s[6:7]
	s_cbranch_execz .LBB0_701
	s_waitcnt lgkmcnt(0)
	v_cvt_pk_bf16_f32 v17, v17, v18
	v_add_co_u32_e32 v18, vcc, 0x9000, v96
	s_nop 1
	v_addc_co_u32_e32 v19, vcc, 0, v97, vcc
	global_store_dword v[18:19], v17, off
.LBB0_701:
	s_or_b64 exec, exec, s[18:19]
	v_mul_f32_e32 v17, v74, v16
	s_waitcnt lgkmcnt(0)
	s_nop 1
	v_mov_b32_dpp v18, v17 quad_perm:[1,0,3,2] row_mask:0xf bank_mask:0xf
	s_and_saveexec_b64 s[18:19], s[6:7]
	s_cbranch_execz .LBB0_703
	s_waitcnt lgkmcnt(0)
	v_cvt_pk_bf16_f32 v17, v17, v18
	v_add_co_u32_e32 v18, vcc, 0x9000, v96
	s_nop 1
	v_addc_co_u32_e32 v19, vcc, 0, v97, vcc
	global_store_dword v[18:19], v17, off offset:64
.LBB0_703:
	s_or_b64 exec, exec, s[18:19]
	v_mul_f32_e32 v17, v42, v16
	s_waitcnt lgkmcnt(0)
	s_nop 1
	v_mov_b32_dpp v18, v17 quad_perm:[1,0,3,2] row_mask:0xf bank_mask:0xf
	s_and_saveexec_b64 s[18:19], s[6:7]
	s_cbranch_execz .LBB0_705
	s_waitcnt lgkmcnt(0)
	v_cvt_pk_bf16_f32 v17, v17, v18
	v_add_co_u32_e32 v18, vcc, 0x9000, v96
	s_nop 1
	v_addc_co_u32_e32 v19, vcc, 0, v97, vcc
	global_store_dword v[18:19], v17, off offset:128
.LBB0_705:
	s_or_b64 exec, exec, s[18:19]
	v_mul_f32_e32 v16, v26, v16
	s_nop 1
	v_mov_b32_dpp v17, v16 quad_perm:[1,0,3,2] row_mask:0xf bank_mask:0xf
	s_and_saveexec_b64 s[18:19], s[6:7]
	s_cbranch_execz .LBB0_707
	s_waitcnt lgkmcnt(0)
	v_cvt_pk_bf16_f32 v18, v16, v17
	v_add_co_u32_e32 v16, vcc, 0x9000, v96
	s_nop 1
	v_addc_co_u32_e32 v17, vcc, 0, v97, vcc
	global_store_dword v[16:17], v18, off offset:192
.LBB0_707:
	s_or_b64 exec, exec, s[18:19]
	v_rcp_f32_e32 v16, v87
	s_waitcnt lgkmcnt(0)
	v_mul_f32_e32 v17, v59, v16
	s_nop 1
	v_mov_b32_dpp v18, v17 quad_perm:[1,0,3,2] row_mask:0xf bank_mask:0xf
	s_and_saveexec_b64 s[18:19], s[6:7]
	s_cbranch_execz .LBB0_709
	s_waitcnt lgkmcnt(0)
	v_cvt_pk_bf16_f32 v17, v17, v18
	v_add_co_u32_e32 v18, vcc, 0x9000, v96
	s_nop 1
	v_addc_co_u32_e32 v19, vcc, 0, v97, vcc
	global_store_dword v[18:19], v17, off offset:2048
.LBB0_709:
	s_or_b64 exec, exec, s[18:19]
	v_mul_f32_e32 v17, v75, v16
	s_waitcnt lgkmcnt(0)
	s_nop 1
	v_mov_b32_dpp v18, v17 quad_perm:[1,0,3,2] row_mask:0xf bank_mask:0xf
	s_and_saveexec_b64 s[18:19], s[6:7]
	s_cbranch_execz .LBB0_711
	s_waitcnt lgkmcnt(0)
	v_cvt_pk_bf16_f32 v17, v17, v18
	v_add_co_u32_e32 v18, vcc, 0x9000, v96
	s_nop 1
	v_addc_co_u32_e32 v19, vcc, 0, v97, vcc
	global_store_dword v[18:19], v17, off offset:2112
.LBB0_711:
	s_or_b64 exec, exec, s[18:19]
	v_mul_f32_e32 v17, v43, v16
	s_waitcnt lgkmcnt(0)
	s_nop 1
	v_mov_b32_dpp v18, v17 quad_perm:[1,0,3,2] row_mask:0xf bank_mask:0xf
	s_and_saveexec_b64 s[18:19], s[6:7]
	s_cbranch_execz .LBB0_713
	s_waitcnt lgkmcnt(0)
	v_cvt_pk_bf16_f32 v17, v17, v18
	v_add_co_u32_e32 v18, vcc, 0x9000, v96
	s_nop 1
	v_addc_co_u32_e32 v19, vcc, 0, v97, vcc
	global_store_dword v[18:19], v17, off offset:2176
; __device__ __forceinline__ int crow(int r, int hi) { return (r & 3) + 8 * (r >> 2) + 4 * hi; }
; template <typename TQ>
; __device__ __forceinline__ void attn_dense_body(const TQ* __restrict__ Qb, const bf16* __restrict__ Kh, const bf16* __restrict__ Vh,
;                                                 bf16* __restrict__ Ob, int seq, char* lds, float mraw) {
;     ...
;   for (int r = 0; r < 16; ++r) { int orow = crow(r, hi);
; #pragma unroll
;     for (int d0 = 0; d0 < 4; ++d0) { const float v = o[d0][r] * rli[r]; const float nb = __shfl_xor(v, 1);
;       if (!(r32 & 1)) *reinterpret_cast<unsigned*>(Ow + (long)orow * LDO + d0 * 32 + r32) = cvtpk(v, nb); } }
.LBB0_713:
	s_or_b64 exec, exec, s[18:19]
	v_mul_f32_e32 v16, v27, v16
	s_nop 1
	v_mov_b32_dpp v17, v16 quad_perm:[1,0,3,2] row_mask:0xf bank_mask:0xf
	s_and_saveexec_b64 s[18:19], s[6:7]
	s_cbranch_execz .LBB0_715
	s_waitcnt lgkmcnt(0)
	v_cvt_pk_bf16_f32 v18, v16, v17
	v_add_co_u32_e32 v16, vcc, 0x9000, v96
	s_nop 1
	v_addc_co_u32_e32 v17, vcc, 0, v97, vcc
	global_store_dword v[16:17], v18, off offset:2240
.LBB0_715:
	s_or_b64 exec, exec, s[18:19]
	v_rcp_f32_e32 v16, v80
	s_waitcnt lgkmcnt(0)
	v_mul_f32_e32 v17, v60, v16
	s_nop 1
	v_mov_b32_dpp v18, v17 quad_perm:[1,0,3,2] row_mask:0xf bank_mask:0xf
	s_and_saveexec_b64 s[18:19], s[6:7]
	s_cbranch_execz .LBB0_717
	s_waitcnt lgkmcnt(0)
	v_cvt_pk_bf16_f32 v17, v17, v18
	v_add_co_u32_e32 v18, vcc, 0xc000, v96
	s_nop 1
	v_addc_co_u32_e32 v19, vcc, 0, v97, vcc
	global_store_dword v[18:19], v17, off
.LBB0_717:
	s_or_b64 exec, exec, s[18:19]
	v_mul_f32_e32 v17, v76, v16
	s_waitcnt lgkmcnt(0)
	s_nop 1
	v_mov_b32_dpp v18, v17 quad_perm:[1,0,3,2] row_mask:0xf bank_mask:0xf
	s_and_saveexec_b64 s[18:19], s[6:7]
	s_cbranch_execz .LBB0_719
	s_waitcnt lgkmcnt(0)
	v_cvt_pk_bf16_f32 v17, v17, v18
	v_add_co_u32_e32 v18, vcc, 0xc000, v96
	s_nop 1
	v_addc_co_u32_e32 v19, vcc, 0, v97, vcc
	global_store_dword v[18:19], v17, off offset:64
.LBB0_719:
	s_or_b64 exec, exec, s[18:19]
	v_mul_f32_e32 v17, v44, v16
	s_waitcnt lgkmcnt(0)
	s_nop 1
	v_mov_b32_dpp v18, v17 quad_perm:[1,0,3,2] row_mask:0xf bank_mask:0xf
	s_and_saveexec_b64 s[18:19], s[6:7]
	s_cbranch_execz .LBB0_721
	s_waitcnt lgkmcnt(0)
	v_cvt_pk_bf16_f32 v17, v17, v18
	v_add_co_u32_e32 v18, vcc, 0xc000, v96
	s_nop 1
	v_addc_co_u32_e32 v19, vcc, 0, v97, vcc
	global_store_dword v[18:19], v17, off offset:128
.LBB0_721:
	s_or_b64 exec, exec, s[18:19]
	v_mul_f32_e32 v16, v28, v16
	s_nop 1
	v_mov_b32_dpp v17, v16 quad_perm:[1,0,3,2] row_mask:0xf bank_mask:0xf
	s_and_saveexec_b64 s[18:19], s[6:7]
	s_cbranch_execz .LBB0_723
	s_waitcnt lgkmcnt(0)
	v_cvt_pk_bf16_f32 v18, v16, v17
	v_add_co_u32_e32 v16, vcc, 0xc000, v96
	s_nop 1
	v_addc_co_u32_e32 v17, vcc, 0, v97, vcc
	global_store_dword v[16:17], v18, off offset:192
.LBB0_723:
	s_or_b64 exec, exec, s[18:19]
	v_rcp_f32_e32 v16, v81
	s_waitcnt lgkmcnt(0)
	v_mul_f32_e32 v17, v61, v16
	s_nop 1
	v_mov_b32_dpp v18, v17 quad_perm:[1,0,3,2] row_mask:0xf bank_mask:0xf
	s_and_saveexec_b64 s[18:19], s[6:7]
	s_cbranch_execz .LBB0_725
	s_waitcnt lgkmcnt(0)
	v_cvt_pk_bf16_f32 v17, v17, v18
	v_add_co_u32_e32 v18, vcc, 0xc000, v96
	s_nop 1
	v_addc_co_u32_e32 v19, vcc, 0, v97, vcc
	global_store_dword v[18:19], v17, off offset:2048
.LBB0_725:
	s_or_b64 exec, exec, s[18:19]
	v_mul_f32_e32 v17, v77, v16
	s_waitcnt lgkmcnt(0)
	s_nop 1
	v_mov_b32_dpp v18, v17 quad_perm:[1,0,3,2] row_mask:0xf bank_mask:0xf
	s_and_saveexec_b64 s[18:19], s[6:7]
	s_cbranch_execz .LBB0_727
	s_waitcnt lgkmcnt(0)
	v_cvt_pk_bf16_f32 v17, v17, v18
	v_add_co_u32_e32 v18, vcc, 0xc000, v96
	s_nop 1
	v_addc_co_u32_e32 v19, vcc, 0, v97, vcc
	global_store_dword v[18:19], v17, off offset:2112
.LBB0_727:
	s_or_b64 exec, exec, s[18:19]
	v_mul_f32_e32 v17, v45, v16
	s_waitcnt lgkmcnt(0)
	s_nop 1
	v_mov_b32_dpp v18, v17 quad_perm:[1,0,3,2] row_mask:0xf bank_mask:0xf
	s_and_saveexec_b64 s[18:19], s[6:7]
	s_cbranch_execz .LBB0_729
	s_waitcnt lgkmcnt(0)
	v_cvt_pk_bf16_f32 v17, v17, v18
	v_add_co_u32_e32 v18, vcc, 0xc000, v96
	s_nop 1
	v_addc_co_u32_e32 v19, vcc, 0, v97, vcc
	global_store_dword v[18:19], v17, off offset:2176
.LBB0_729:
	s_or_b64 exec, exec, s[18:19]
	v_mul_f32_e32 v16, v29, v16
	s_nop 1
	v_mov_b32_dpp v17, v16 quad_perm:[1,0,3,2] row_mask:0xf bank_mask:0xf
	s_and_saveexec_b64 s[18:19], s[6:7]
	s_cbranch_execz .LBB0_731
	s_waitcnt lgkmcnt(0)
	v_cvt_pk_bf16_f32 v18, v16, v17
	v_add_co_u32_e32 v16, vcc, 0xc000, v96
	s_nop 1
	v_addc_co_u32_e32 v17, vcc, 0, v97, vcc
	global_store_dword v[16:17], v18, off offset:2240
; __device__ __forceinline__ int crow(int r, int hi) { return (r & 3) + 8 * (r >> 2) + 4 * hi; }
; template <typename TQ>
; __device__ __forceinline__ void attn_dense_body(const TQ* __restrict__ Qb, const bf16* __restrict__ Kh, const bf16* __restrict__ Vh,
;                                                 bf16* __restrict__ Ob, int seq, char* lds, float mraw) {
;     ...
;   for (int r = 0; r < 16; ++r) { int orow = crow(r, hi);
; #pragma unroll
;     for (int d0 = 0; d0 < 4; ++d0) { const float v = o[d0][r] * rli[r]; const float nb = __shfl_xor(v, 1);
;       if (!(r32 & 1)) *reinterpret_cast<unsigned*>(Ow + (long)orow * LDO + d0 * 32 + r32) = cvtpk(v, nb); } }
.LBB0_731:
	s_or_b64 exec, exec, s[18:19]
	v_rcp_f32_e32 v16, v82
	s_waitcnt lgkmcnt(0)
	v_mul_f32_e32 v17, v62, v16
	s_nop 1
	v_mov_b32_dpp v18, v17 quad_perm:[1,0,3,2] row_mask:0xf bank_mask:0xf
	s_and_saveexec_b64 s[18:19], s[6:7]
	s_cbranch_execz .LBB0_733
	s_waitcnt lgkmcnt(0)
	v_cvt_pk_bf16_f32 v17, v17, v18
	v_add_co_u32_e32 v18, vcc, 0xd000, v96
	s_nop 1
	v_addc_co_u32_e32 v19, vcc, 0, v97, vcc
	global_store_dword v[18:19], v17, off
.LBB0_733:
	s_or_b64 exec, exec, s[18:19]
	v_mul_f32_e32 v17, v78, v16
	s_waitcnt lgkmcnt(0)
	s_nop 1
	v_mov_b32_dpp v18, v17 quad_perm:[1,0,3,2] row_mask:0xf bank_mask:0xf
	s_and_saveexec_b64 s[18:19], s[6:7]
	s_cbranch_execz .LBB0_735
	s_waitcnt lgkmcnt(0)
	v_cvt_pk_bf16_f32 v17, v17, v18
	v_add_co_u32_e32 v18, vcc, 0xd000, v96
	s_nop 1
	v_addc_co_u32_e32 v19, vcc, 0, v97, vcc
	global_store_dword v[18:19], v17, off offset:64
.LBB0_735:
	s_or_b64 exec, exec, s[18:19]
	v_mul_f32_e32 v17, v46, v16
	s_waitcnt lgkmcnt(0)
	s_nop 1
	v_mov_b32_dpp v18, v17 quad_perm:[1,0,3,2] row_mask:0xf bank_mask:0xf
	s_and_saveexec_b64 s[18:19], s[6:7]
	s_cbranch_execz .LBB0_737
	s_waitcnt lgkmcnt(0)
	v_cvt_pk_bf16_f32 v17, v17, v18
	v_add_co_u32_e32 v18, vcc, 0xd000, v96
	s_nop 1
	v_addc_co_u32_e32 v19, vcc, 0, v97, vcc
	global_store_dword v[18:19], v17, off offset:128
.LBB0_737:
	s_or_b64 exec, exec, s[18:19]
	v_mul_f32_e32 v16, v30, v16
	s_nop 1
	v_mov_b32_dpp v17, v16 quad_perm:[1,0,3,2] row_mask:0xf bank_mask:0xf
	s_and_saveexec_b64 s[18:19], s[6:7]
	s_cbranch_execz .LBB0_739
	s_waitcnt lgkmcnt(0)
	v_cvt_pk_bf16_f32 v18, v16, v17
	v_add_co_u32_e32 v16, vcc, 0xd000, v96
	s_nop 1
	v_addc_co_u32_e32 v17, vcc, 0, v97, vcc
	global_store_dword v[16:17], v18, off offset:192
.LBB0_739:
	s_or_b64 exec, exec, s[18:19]
	v_rcp_f32_e32 v16, v83
	s_waitcnt lgkmcnt(0)
	v_mul_f32_e32 v17, v63, v16
	s_nop 1
	v_mov_b32_dpp v18, v17 quad_perm:[1,0,3,2] row_mask:0xf bank_mask:0xf
	s_and_saveexec_b64 s[18:19], s[6:7]
	s_cbranch_execz .LBB0_741
	s_waitcnt lgkmcnt(0)
	v_cvt_pk_bf16_f32 v17, v17, v18
	v_add_co_u32_e32 v18, vcc, 0xd000, v96
	s_nop 1
	v_addc_co_u32_e32 v19, vcc, 0, v97, vcc
	global_store_dword v[18:19], v17, off offset:2048
.LBB0_741:
	s_or_b64 exec, exec, s[18:19]
	v_mul_f32_e32 v17, v79, v16
	s_waitcnt lgkmcnt(0)
	s_nop 1
	v_mov_b32_dpp v18, v17 quad_perm:[1,0,3,2] row_mask:0xf bank_mask:0xf
	s_and_saveexec_b64 s[18:19], s[6:7]
	s_cbranch_execz .LBB0_743
	s_waitcnt lgkmcnt(0)
	v_cvt_pk_bf16_f32 v17, v17, v18
	v_add_co_u32_e32 v18, vcc, 0xd000, v96
	s_nop 1
	v_addc_co_u32_e32 v19, vcc, 0, v97, vcc
	global_store_dword v[18:19], v17, off offset:2112
.LBB0_743:
	s_or_b64 exec, exec, s[18:19]
	v_mul_f32_e32 v17, v47, v16
	s_waitcnt lgkmcnt(0)
	s_nop 1
	v_mov_b32_dpp v18, v17 quad_perm:[1,0,3,2] row_mask:0xf bank_mask:0xf
	s_and_saveexec_b64 s[18:19], s[6:7]
	s_cbranch_execz .LBB0_745
	s_waitcnt lgkmcnt(0)
	v_cvt_pk_bf16_f32 v17, v17, v18
	v_add_co_u32_e32 v18, vcc, 0xd000, v96
	s_nop 1
	v_addc_co_u32_e32 v19, vcc, 0, v97, vcc
	global_store_dword v[18:19], v17, off offset:2176
.LBB0_745:
	s_or_b64 exec, exec, s[18:19]
	v_mul_f32_e32 v16, v31, v16
	s_nop 1
	v_mov_b32_dpp v17, v16 quad_perm:[1,0,3,2] row_mask:0xf bank_mask:0xf
	s_and_saveexec_b64 s[18:19], s[6:7]
	s_cbranch_execz .LBB0_591
	s_waitcnt lgkmcnt(0)
	v_cvt_pk_bf16_f32 v18, v16, v17
	v_add_co_u32_e32 v16, vcc, 0xd000, v96
	s_nop 1
	v_addc_co_u32_e32 v17, vcc, 0, v97, vcc
	global_store_dword v[16:17], v18, off offset:2240
	s_branch .LBB0_591
